# input projection, first mixer group: f_a column tiles computed by a short direct MFMA unit and moved (tile-order swap inside each XCD's pair of row groups) into the last partial round
# baseline (speedup 1.0000x reference)
;     __host__ __device__ bool next(int i, Unit& u) const {
;         const long L = (long)i * G + c; if (L >= nwg) return false;
;         int wgid = (int)L; { const int q = nwg / NXCD, r = nwg % NXCD, xcd = wgid % NXCD, off = wgid / NXCD; wgid = (xcd < r ? xcd * (q + 1) : r * (q + 1) + (xcd - r) * q) + off; }
;         const int nig = WGM * nN, gid = wgid / nig, fm = gid * WGM, gsz = (nM - fm) < WGM ? (nM - fm) : WGM;
;         u.pm = fm + ((wgid % nig) % gsz); u.pn = (wgid % nig) / gsz; return true;
.LBB0_361:
	s_ashr_i32 s6, s6, 3
	s_add_i32 s6, s11, s6
	s_mul_hi_i32 s7, s6, 0x3e0f83e1
	s_lshr_b32 s11, s7, 31
	s_ashr_i32 s7, s7, 5
	s_add_i32 s7, s7, s11
	s_lshl_b32 s11, s7, 2
	s_sub_i32 s13, s2, s11
	s_min_i32 s13, s13, 4
	s_abs_i32 s26, s13
	v_cvt_f32_u32_e32 v2, s26
	s_sub_i32 s28, 0, s26
	s_mulk_i32 s7, 0x84
	s_sub_i32 s6, s6, s7
	v_rcp_iflag_f32_e32 v2, v2
	s_abs_i32 s7, s6
	s_xor_b32 s27, s6, s13
	s_ashr_i32 s27, s27, 31
	v_mul_f32_e32 v2, 0x4f7ffffe, v2
	v_cvt_u32_f32_e32 v2, v2
	s_nop 0
	v_readfirstlane_b32 s29, v2
	s_mul_i32 s28, s28, s29
	s_mul_hi_u32 s28, s29, s28
	s_add_i32 s29, s29, s28
	s_mul_hi_u32 s28, s7, s29
	s_mul_i32 s29, s28, s26
	s_sub_i32 s7, s7, s29
	s_add_i32 s30, s28, 1
	s_sub_i32 s29, s7, s26
	s_cmp_ge_u32 s7, s26
	s_cselect_b32 s28, s30, s28
	s_cselect_b32 s7, s29, s7
	s_add_i32 s29, s28, 1
	s_cmp_ge_u32 s7, s26
	s_cselect_b32 s7, s29, s28
	s_xor_b32 s7, s7, s27
	s_sub_i32 s26, s7, s27
	s_mul_i32 s7, s26, s13
	s_sub_i32 s6, s6, s7
	s_add_i32 s28, s11, s6
	s_cmp_lg_u32 s2, 64
	s_cbranch_scc1 .LBB0_362
	s_bitcmp1_b32 s28, 2
	s_cbranch_scc1 .Lp3_odd_grp
	s_cmp_lg_u32 s26, 32
	s_cbranch_scc1 .LBB0_362
	s_add_i32 s28, s28, 4
	s_mov_b32 s26, 31
	s_branch .LBB0_362
.Lp3_odd_grp:
	s_cmp_lg_u32 s26, 31
	s_cbranch_scc1 .LBB0_362
	s_sub_i32 s28, s28, 4
	s_mov_b32 s26, 32

; __device__ __forceinline__ float rstd_from_ss(const float* ssrow, int fq) {
;     const f32x4 a = ((const f32x4*)ssrow)[fq];
;     float s = (a[0] + a[1]) + (a[2] + a[3]);
;     s += __shfl_xor(s, 16); s += __shfl_xor(s, 32);
;     return rsqrtf(s * (1.0f / 1024.0f) + 1e-6f);
; }
;     __device__ __forceinline__ void operator()(const f32x4 (&acc)[2][2][4][2], const Unit& u, int wr, int wc, int fr, int fq) const {
;         const int pn = u.pn; const int lrow0 = u.pm * BM + wr * 64 + fr;
;         bf16_t* dst; int ldc, colt;
;         if (pn < 24) { dst = PB + (size_t)(pn >> 2) * pbs; ldc = 1024; colt = (pn & 3) * 256; } else { dst = GG; ldc = 2048; colt = (pn - 24) * 256; }
;         const int col0 = colt + wc * 32 + 8 * fq;
;         float* kvo = nullptr; long kvrow0 = 0;
;         if (pn >= 16 && pn < 24) {
;             const int gt = grow0 + u.pm * BM;
;             if (gt >= 32768) { kvo = (pn < 20) ? oks : ovs; kvrow0 = (long)(gt - 32768) - (long)(u.pm * BM); }
;             else if ((gt & 2047) >= 1536) { kvo = (pn < 20) ? okp : ovp; kvrow0 = (long)((gt >> 11) * 512 + ((gt & 2047) - 1536)) - (long)(u.pm * BM); }
;         }
; #pragma unroll
;         for (int ai = 0; ai < 2; ++ai)
; #pragma unroll
;             for (int m = 0; m < 4; ++m) {
;                 int row = lrow0 + ai * HALF + m * 16; asm volatile("" : "+v"(row));
;                 const float rs = rstd_from_ss(SS + (size_t)row * 16, fq);
.LBB0_374:
	s_cmp_eq_u32 s10, 32
	s_cbranch_scc1 .Lfa_unit
	v_add_u32_e32 v170, s7, v166
	v_ashrrev_i32_e32 v171, 31, v170
	v_lshlrev_b64 v[172:173], 6, v[170:171]
	s_mov_b64 s[40:41], 0x2000
	v_lshl_add_u64 v[172:173], v[146:147], 0, v[172:173]
	v_add_u32_e32 v2, s6, v168
	v_lshl_add_u64 v[174:175], v[172:173], 0, s[40:41]
	global_load_dwordx4 v[210:213], v[172:173], off
	global_load_dwordx4 v[214:217], v[172:173], off offset:1024
	global_load_dwordx4 v[218:221], v[172:173], off offset:2048
	global_load_dwordx4 v[222:225], v[172:173], off offset:3072
	global_load_dwordx4 v[226:229], v[174:175], off
	global_load_dwordx4 v[230:233], v[174:175], off offset:1024
	global_load_dwordx4 v[234:237], v[174:175], off offset:2048
	global_load_dwordx4 v[238:241], v[174:175], off offset:3072
	v_lshl_add_u64 v[156:157], v[2:3], 1, s[14:15]
	v_mad_i64_i32 v[160:161], s[42:43], s36, v170, 0
	v_lshl_add_u64 v[158:159], v[2:3], 2, s[12:13]
	v_lshl_add_u64 v[162:163], s[38:39], 0, v[170:171]
	v_lshl_add_u64 v[156:157], v[160:161], 1, v[156:157]
	v_lshlrev_b64 v[162:163], 12, v[162:163]
	v_lshlrev_b64 v[160:161], 6, v[170:171]
	v_lshl_add_u64 v[158:159], v[158:159], 0, v[162:163]
	v_lshl_add_u64 v[160:161], v[148:149], 0, v[160:161]
	v_lshl_add_u64 v[162:163], v[160:161], 0, s[40:41]
	s_waitcnt vmcnt(4)
	v_add_f32_e32 v210, v211, v210
	v_add_f32_e32 v214, v215, v214
	v_add_f32_e32 v218, v219, v218
	v_add_f32_e32 v222, v223, v222
	v_add_f32_e32 v212, v212, v213
	v_add_f32_e32 v216, v216, v217
	v_add_f32_e32 v220, v220, v221
	v_add_f32_e32 v224, v224, v225
	v_add_f32_e32 v210, v210, v212
	v_add_f32_e32 v214, v214, v216
	v_add_f32_e32 v218, v218, v220
	v_add_f32_e32 v222, v222, v224
	ds_bpermute_b32 v211, v199, v210
	ds_bpermute_b32 v215, v199, v214
	ds_bpermute_b32 v219, v199, v218
	ds_bpermute_b32 v223, v199, v222
	s_waitcnt vmcnt(0)
	v_add_f32_e32 v226, v227, v226
	v_add_f32_e32 v230, v231, v230
	v_add_f32_e32 v234, v235, v234
	v_add_f32_e32 v238, v239, v238
	v_add_f32_e32 v228, v228, v229
	v_add_f32_e32 v232, v232, v233
	v_add_f32_e32 v236, v236, v237
	v_add_f32_e32 v240, v240, v241
	v_add_f32_e32 v226, v226, v228
	v_add_f32_e32 v230, v230, v232
	v_add_f32_e32 v234, v234, v236
	v_add_f32_e32 v238, v238, v240
	ds_bpermute_b32 v227, v199, v226
	ds_bpermute_b32 v231, v199, v230
	ds_bpermute_b32 v235, v199, v234
	ds_bpermute_b32 v239, v199, v238
	s_waitcnt lgkmcnt(4)
	v_add_f32_e32 v210, v210, v211
	v_add_f32_e32 v214, v214, v215
	v_add_f32_e32 v218, v218, v219
	v_add_f32_e32 v222, v222, v223
	ds_bpermute_b32 v211, v200, v210
	ds_bpermute_b32 v215, v200, v214
	ds_bpermute_b32 v219, v200, v218
	ds_bpermute_b32 v223, v200, v222
	s_waitcnt lgkmcnt(4)
	v_add_f32_e32 v226, v226, v227
	v_add_f32_e32 v230, v230, v231
	v_add_f32_e32 v234, v234, v235
	v_add_f32_e32 v238, v238, v239
	ds_bpermute_b32 v227, v200, v226
	ds_bpermute_b32 v231, v200, v230
	ds_bpermute_b32 v235, v200, v234
	ds_bpermute_b32 v239, v200, v238
	s_waitcnt lgkmcnt(4)
	v_add_f32_e32 v210, v210, v211
	v_add_f32_e32 v214, v214, v215
	v_add_f32_e32 v218, v218, v219
	v_add_f32_e32 v222, v222, v223
	v_fmamk_f32 v210, v210, 0x3a800000, v140
	v_fmamk_f32 v214, v214, 0x3a800000, v140
	v_fmamk_f32 v218, v218, 0x3a800000, v140
	v_fmamk_f32 v222, v222, 0x3a800000, v140
	v_cmp_gt_f32_e64 vcc, s92, v210
	v_cmp_gt_f32_e64 s[6:7], s92, v214
	v_cmp_gt_f32_e64 s[40:41], s92, v218
	v_cmp_gt_f32_e64 s[42:43], s92, v222
	v_mul_f32_e32 v211, 0x4b800000, v210
	v_mul_f32_e32 v215, 0x4b800000, v214
	v_mul_f32_e32 v219, 0x4b800000, v218
	v_mul_f32_e32 v223, 0x4b800000, v222
	v_cndmask_b32_e64 v210, v210, v211, vcc
	v_cndmask_b32_e64 v214, v214, v215, s[6:7]
	v_cndmask_b32_e64 v218, v218, v219, s[40:41]
	v_cndmask_b32_e64 v222, v222, v223, s[42:43]
	v_rsq_f32_e32 v210, v210
	v_rsq_f32_e32 v214, v214
	v_rsq_f32_e32 v218, v218
	v_rsq_f32_e32 v222, v222
	v_mul_f32_e32 v211, 0x45800000, v210
	v_mul_f32_e32 v215, 0x45800000, v214
	v_mul_f32_e32 v219, 0x45800000, v218
	v_mul_f32_e32 v223, 0x45800000, v222
	v_cndmask_b32_e64 v210, v210, v211, vcc
	v_cndmask_b32_e64 v214, v214, v215, s[6:7]
	v_cndmask_b32_e64 v218, v218, v219, s[40:41]
	v_cndmask_b32_e64 v222, v222, v223, s[42:43]
	s_waitcnt lgkmcnt(0)
	v_add_f32_e32 v226, v226, v227
	v_add_f32_e32 v230, v230, v231
	v_add_f32_e32 v234, v234, v235
	v_add_f32_e32 v238, v238, v239
	v_fmamk_f32 v226, v226, 0x3a800000, v140
	v_fmamk_f32 v230, v230, 0x3a800000, v140
	v_fmamk_f32 v234, v234, 0x3a800000, v140
	v_fmamk_f32 v238, v238, 0x3a800000, v140
	v_cmp_gt_f32_e64 vcc, s92, v226
	v_cmp_gt_f32_e64 s[6:7], s92, v230
	v_cmp_gt_f32_e64 s[40:41], s92, v234
	v_cmp_gt_f32_e64 s[42:43], s92, v238
	v_mul_f32_e32 v227, 0x4b800000, v226
	v_mul_f32_e32 v231, 0x4b800000, v230
	v_mul_f32_e32 v235, 0x4b800000, v234
	v_mul_f32_e32 v239, 0x4b800000, v238
	v_cndmask_b32_e64 v226, v226, v227, vcc
	v_cndmask_b32_e64 v230, v230, v231, s[6:7]
	v_cndmask_b32_e64 v234, v234, v235, s[40:41]
	v_cndmask_b32_e64 v238, v238, v239, s[42:43]
	v_rsq_f32_e32 v226, v226
	v_rsq_f32_e32 v230, v230
	v_rsq_f32_e32 v234, v234
	v_rsq_f32_e32 v238, v238
	v_mul_f32_e32 v227, 0x45800000, v226
	v_mul_f32_e32 v231, 0x45800000, v230
	v_mul_f32_e32 v235, 0x45800000, v234
	v_mul_f32_e32 v239, 0x45800000, v238
	v_cndmask_b32_e64 v226, v226, v227, vcc
	v_cndmask_b32_e64 v230, v230, v231, s[6:7]
	v_cndmask_b32_e64 v234, v234, v235, s[40:41]
	v_cndmask_b32_e64 v238, v238, v239, s[42:43]
	s_cmp_gt_i32 s10, 31
	s_cbranch_scc1 .Lp3e_fa
	s_lshl_b32 s40, s36, 5
	s_mov_b32 s41, 0
	s_mul_i32 s42, s36, 0xa0
	s_mov_b32 s43, 0
	s_cmp_lg_u64 s[12:13], 0
	s_cbranch_scc1 .Lp3e_kv
; __device__ __forceinline__ unsigned cvt_pk_bf16(float lo, float hi) { f32x2_cv v = {lo, hi}; bf16x2_cv b = __builtin_convertvector(v, bf16x2_cv); return __builtin_bit_cast(unsigned, b); }
;     __device__ __forceinline__ void operator()(const f32x4 (&acc)[2][2][4][2], const Unit& u, int wr, int wc, int fr, int fq) const {
;     ...
;                 int row = lrow0 + ai * HALF + m * 16; asm volatile("" : "+v"(row));
;                 const float rs = rstd_from_ss(SS + (size_t)row * 16, fq);
;                 if (pn < 32) {
; #pragma unroll
;                     for (int bj = 0; bj < 2; ++bj) {
;                         const f32x4 v0 = acc[ai][bj][m][0] * rs, v1 = acc[ai][bj][m][1] * rs;
;                         u32x4 w; w.x = cvt_pk_bf16(v0[0], v0[1]); w.y = cvt_pk_bf16(v0[2], v0[3]); w.z = cvt_pk_bf16(v1[0], v1[1]); w.w = cvt_pk_bf16(v1[2], v1[3]);
;                         if (pn >= 24) __builtin_nontemporal_store(w, (u32x4*)(dst + (size_t)row * ldc + col0 + bj * HALF)); else *(u32x4*)(dst + (size_t)row * ldc + col0 + bj * HALF) = w;
	v_pk_mul_f32 v[128:129], v[128:129], v[210:211] op_sel_hi:[1,0]
	v_pk_mul_f32 v[130:131], v[130:131], v[210:211] op_sel_hi:[1,0]
	v_pk_mul_f32 v[124:125], v[124:125], v[210:211] op_sel_hi:[1,0]
	v_pk_mul_f32 v[126:127], v[126:127], v[210:211] op_sel_hi:[1,0]
	v_cvt_pk_bf16_f32 v182, v128, v129
	v_cvt_pk_bf16_f32 v183, v130, v131
	v_cvt_pk_bf16_f32 v184, v124, v125
	v_cvt_pk_bf16_f32 v185, v126, v127
	global_store_dwordx4 v[156:157], v[182:185], off
	v_pk_mul_f32 v[120:121], v[120:121], v[210:211] op_sel_hi:[1,0]
	v_pk_mul_f32 v[122:123], v[122:123], v[210:211] op_sel_hi:[1,0]
	v_pk_mul_f32 v[116:117], v[116:117], v[210:211] op_sel_hi:[1,0]
	v_pk_mul_f32 v[118:119], v[118:119], v[210:211] op_sel_hi:[1,0]
	v_cvt_pk_bf16_f32 v186, v120, v121
	v_cvt_pk_bf16_f32 v187, v122, v123
	v_cvt_pk_bf16_f32 v188, v116, v117
	v_cvt_pk_bf16_f32 v189, v118, v119
	global_store_dwordx4 v[156:157], v[186:189], off offset:256
	v_lshl_add_u64 v[156:157], v[156:157], 0, s[40:41]
	v_pk_mul_f32 v[112:113], v[112:113], v[214:215] op_sel_hi:[1,0]
	v_pk_mul_f32 v[114:115], v[114:115], v[214:215] op_sel_hi:[1,0]
	v_pk_mul_f32 v[108:109], v[108:109], v[214:215] op_sel_hi:[1,0]
	v_pk_mul_f32 v[110:111], v[110:111], v[214:215] op_sel_hi:[1,0]
	v_cvt_pk_bf16_f32 v190, v112, v113
	v_cvt_pk_bf16_f32 v191, v114, v115
	v_cvt_pk_bf16_f32 v192, v108, v109
	v_cvt_pk_bf16_f32 v193, v110, v111
	global_store_dwordx4 v[156:157], v[190:193], off
	v_pk_mul_f32 v[104:105], v[104:105], v[214:215] op_sel_hi:[1,0]
	v_pk_mul_f32 v[106:107], v[106:107], v[214:215] op_sel_hi:[1,0]
	v_pk_mul_f32 v[100:101], v[100:101], v[214:215] op_sel_hi:[1,0]
	v_pk_mul_f32 v[102:103], v[102:103], v[214:215] op_sel_hi:[1,0]
	v_cvt_pk_bf16_f32 v242, v104, v105
	v_cvt_pk_bf16_f32 v243, v106, v107
	v_cvt_pk_bf16_f32 v244, v100, v101
	v_cvt_pk_bf16_f32 v245, v102, v103
	global_store_dwordx4 v[156:157], v[242:245], off offset:256
	v_lshl_add_u64 v[156:157], v[156:157], 0, s[40:41]
	v_pk_mul_f32 v[96:97], v[96:97], v[218:219] op_sel_hi:[1,0]
	v_pk_mul_f32 v[98:99], v[98:99], v[218:219] op_sel_hi:[1,0]
	v_pk_mul_f32 v[92:93], v[92:93], v[218:219] op_sel_hi:[1,0]
	v_pk_mul_f32 v[94:95], v[94:95], v[218:219] op_sel_hi:[1,0]
	v_cvt_pk_bf16_f32 v182, v96, v97
	v_cvt_pk_bf16_f32 v183, v98, v99
	v_cvt_pk_bf16_f32 v184, v92, v93
	v_cvt_pk_bf16_f32 v185, v94, v95
	global_store_dwordx4 v[156:157], v[182:185], off
	v_pk_mul_f32 v[88:89], v[88:89], v[218:219] op_sel_hi:[1,0]
	v_pk_mul_f32 v[90:91], v[90:91], v[218:219] op_sel_hi:[1,0]
	v_pk_mul_f32 v[84:85], v[84:85], v[218:219] op_sel_hi:[1,0]
	v_pk_mul_f32 v[86:87], v[86:87], v[218:219] op_sel_hi:[1,0]
	v_cvt_pk_bf16_f32 v186, v88, v89
	v_cvt_pk_bf16_f32 v187, v90, v91
	v_cvt_pk_bf16_f32 v188, v84, v85
	v_cvt_pk_bf16_f32 v189, v86, v87
	global_store_dwordx4 v[156:157], v[186:189], off offset:256
	v_lshl_add_u64 v[156:157], v[156:157], 0, s[40:41]
	v_pk_mul_f32 v[80:81], v[80:81], v[222:223] op_sel_hi:[1,0]
	v_pk_mul_f32 v[82:83], v[82:83], v[222:223] op_sel_hi:[1,0]
	v_pk_mul_f32 v[76:77], v[76:77], v[222:223] op_sel_hi:[1,0]
	v_pk_mul_f32 v[78:79], v[78:79], v[222:223] op_sel_hi:[1,0]
	v_cvt_pk_bf16_f32 v190, v80, v81
	v_cvt_pk_bf16_f32 v191, v82, v83
	v_cvt_pk_bf16_f32 v192, v76, v77
	v_cvt_pk_bf16_f32 v193, v78, v79
	global_store_dwordx4 v[156:157], v[190:193], off
	v_pk_mul_f32 v[72:73], v[72:73], v[222:223] op_sel_hi:[1,0]
	v_pk_mul_f32 v[74:75], v[74:75], v[222:223] op_sel_hi:[1,0]
	v_pk_mul_f32 v[68:69], v[68:69], v[222:223] op_sel_hi:[1,0]
	v_pk_mul_f32 v[70:71], v[70:71], v[222:223] op_sel_hi:[1,0]
	v_cvt_pk_bf16_f32 v242, v72, v73
	v_cvt_pk_bf16_f32 v243, v74, v75
	v_cvt_pk_bf16_f32 v244, v68, v69
	v_cvt_pk_bf16_f32 v245, v70, v71
	global_store_dwordx4 v[156:157], v[242:245], off offset:256
; __device__ __forceinline__ unsigned cvt_pk_bf16(float lo, float hi) { f32x2_cv v = {lo, hi}; bf16x2_cv b = __builtin_convertvector(v, bf16x2_cv); return __builtin_bit_cast(unsigned, b); }
;     __device__ __forceinline__ void operator()(const f32x4 (&acc)[2][2][4][2], const Unit& u, int wr, int wc, int fr, int fq) const {
;     ...
;                 int row = lrow0 + ai * HALF + m * 16; asm volatile("" : "+v"(row));
;                 const float rs = rstd_from_ss(SS + (size_t)row * 16, fq);
;                 if (pn < 32) {
; #pragma unroll
;                     for (int bj = 0; bj < 2; ++bj) {
;                         const f32x4 v0 = acc[ai][bj][m][0] * rs, v1 = acc[ai][bj][m][1] * rs;
;                         u32x4 w; w.x = cvt_pk_bf16(v0[0], v0[1]); w.y = cvt_pk_bf16(v0[2], v0[3]); w.z = cvt_pk_bf16(v1[0], v1[1]); w.w = cvt_pk_bf16(v1[2], v1[3]);
;                         if (pn >= 24) __builtin_nontemporal_store(w, (u32x4*)(dst + (size_t)row * ldc + col0 + bj * HALF)); else *(u32x4*)(dst + (size_t)row * ldc + col0 + bj * HALF) = w;
	v_lshl_add_u64 v[156:157], v[156:157], 0, s[42:43]
	v_pk_mul_f32 v[64:65], v[64:65], v[226:227] op_sel_hi:[1,0]
	v_pk_mul_f32 v[66:67], v[66:67], v[226:227] op_sel_hi:[1,0]
	v_pk_mul_f32 v[60:61], v[60:61], v[226:227] op_sel_hi:[1,0]
	v_pk_mul_f32 v[62:63], v[62:63], v[226:227] op_sel_hi:[1,0]
	v_cvt_pk_bf16_f32 v182, v64, v65
	v_cvt_pk_bf16_f32 v183, v66, v67
	v_cvt_pk_bf16_f32 v184, v60, v61
	v_cvt_pk_bf16_f32 v185, v62, v63
	global_store_dwordx4 v[156:157], v[182:185], off
	v_pk_mul_f32 v[56:57], v[56:57], v[226:227] op_sel_hi:[1,0]
	v_pk_mul_f32 v[58:59], v[58:59], v[226:227] op_sel_hi:[1,0]
	v_pk_mul_f32 v[52:53], v[52:53], v[226:227] op_sel_hi:[1,0]
	v_pk_mul_f32 v[54:55], v[54:55], v[226:227] op_sel_hi:[1,0]
	v_cvt_pk_bf16_f32 v186, v56, v57
	v_cvt_pk_bf16_f32 v187, v58, v59
	v_cvt_pk_bf16_f32 v188, v52, v53
	v_cvt_pk_bf16_f32 v189, v54, v55
	global_store_dwordx4 v[156:157], v[186:189], off offset:256
	v_lshl_add_u64 v[156:157], v[156:157], 0, s[40:41]
	v_pk_mul_f32 v[48:49], v[48:49], v[230:231] op_sel_hi:[1,0]
	v_pk_mul_f32 v[50:51], v[50:51], v[230:231] op_sel_hi:[1,0]
	v_pk_mul_f32 v[44:45], v[44:45], v[230:231] op_sel_hi:[1,0]
	v_pk_mul_f32 v[46:47], v[46:47], v[230:231] op_sel_hi:[1,0]
	v_cvt_pk_bf16_f32 v190, v48, v49
	v_cvt_pk_bf16_f32 v191, v50, v51
	v_cvt_pk_bf16_f32 v192, v44, v45
	v_cvt_pk_bf16_f32 v193, v46, v47
	global_store_dwordx4 v[156:157], v[190:193], off
	v_pk_mul_f32 v[40:41], v[40:41], v[230:231] op_sel_hi:[1,0]
	v_pk_mul_f32 v[42:43], v[42:43], v[230:231] op_sel_hi:[1,0]
	v_pk_mul_f32 v[36:37], v[36:37], v[230:231] op_sel_hi:[1,0]
	v_pk_mul_f32 v[38:39], v[38:39], v[230:231] op_sel_hi:[1,0]
	v_cvt_pk_bf16_f32 v242, v40, v41
	v_cvt_pk_bf16_f32 v243, v42, v43
	v_cvt_pk_bf16_f32 v244, v36, v37
	v_cvt_pk_bf16_f32 v245, v38, v39
	global_store_dwordx4 v[156:157], v[242:245], off offset:256
	v_lshl_add_u64 v[156:157], v[156:157], 0, s[40:41]
	v_pk_mul_f32 v[32:33], v[32:33], v[234:235] op_sel_hi:[1,0]
	v_pk_mul_f32 v[34:35], v[34:35], v[234:235] op_sel_hi:[1,0]
	v_pk_mul_f32 v[28:29], v[28:29], v[234:235] op_sel_hi:[1,0]
	v_pk_mul_f32 v[30:31], v[30:31], v[234:235] op_sel_hi:[1,0]
	v_cvt_pk_bf16_f32 v182, v32, v33
	v_cvt_pk_bf16_f32 v183, v34, v35
	v_cvt_pk_bf16_f32 v184, v28, v29
	v_cvt_pk_bf16_f32 v185, v30, v31
	global_store_dwordx4 v[156:157], v[182:185], off
	v_pk_mul_f32 v[24:25], v[24:25], v[234:235] op_sel_hi:[1,0]
	v_pk_mul_f32 v[26:27], v[26:27], v[234:235] op_sel_hi:[1,0]
	v_pk_mul_f32 v[20:21], v[20:21], v[234:235] op_sel_hi:[1,0]
	v_pk_mul_f32 v[22:23], v[22:23], v[234:235] op_sel_hi:[1,0]
	v_cvt_pk_bf16_f32 v186, v24, v25
	v_cvt_pk_bf16_f32 v187, v26, v27
	v_cvt_pk_bf16_f32 v188, v20, v21
	v_cvt_pk_bf16_f32 v189, v22, v23
	global_store_dwordx4 v[156:157], v[186:189], off offset:256
	v_lshl_add_u64 v[156:157], v[156:157], 0, s[40:41]
	v_pk_mul_f32 v[16:17], v[16:17], v[238:239] op_sel_hi:[1,0]
	v_pk_mul_f32 v[18:19], v[18:19], v[238:239] op_sel_hi:[1,0]
	v_pk_mul_f32 v[12:13], v[12:13], v[238:239] op_sel_hi:[1,0]
	v_pk_mul_f32 v[14:15], v[14:15], v[238:239] op_sel_hi:[1,0]
	v_cvt_pk_bf16_f32 v190, v16, v17
	v_cvt_pk_bf16_f32 v191, v18, v19
	v_cvt_pk_bf16_f32 v192, v12, v13
	v_cvt_pk_bf16_f32 v193, v14, v15
	global_store_dwordx4 v[156:157], v[190:193], off
	v_pk_mul_f32 v[8:9], v[8:9], v[238:239] op_sel_hi:[1,0]
	v_pk_mul_f32 v[10:11], v[10:11], v[238:239] op_sel_hi:[1,0]
	v_pk_mul_f32 v[4:5], v[4:5], v[238:239] op_sel_hi:[1,0]
	v_pk_mul_f32 v[6:7], v[6:7], v[238:239] op_sel_hi:[1,0]
	v_cvt_pk_bf16_f32 v242, v8, v9
	v_cvt_pk_bf16_f32 v243, v10, v11
	v_cvt_pk_bf16_f32 v244, v4, v5
	v_cvt_pk_bf16_f32 v245, v6, v7
	global_store_dwordx4 v[156:157], v[242:245], off offset:256
	s_branch .LBB0_446

; __device__ __forceinline__ unsigned cvt_pk_bf16(float lo, float hi) { f32x2_cv v = {lo, hi}; bf16x2_cv b = __builtin_convertvector(v, bf16x2_cv); return __builtin_bit_cast(unsigned, b); }
;     __device__ __forceinline__ void operator()(const f32x4 (&acc)[2][2][4][2], const Unit& u, int wr, int wc, int fr, int fq) const {
;     ...
;             for (int m = 0; m < 4; ++m) {
;                 int row = lrow0 + ai * HALF + m * 16; asm volatile("" : "+v"(row));
;                 const float rs = rstd_from_ss(SS + (size_t)row * 16, fq);
;                 if (pn < 32) {
; #pragma unroll
;                     for (int bj = 0; bj < 2; ++bj) {
;                         const f32x4 v0 = acc[ai][bj][m][0] * rs, v1 = acc[ai][bj][m][1] * rs;
;                         u32x4 w; w.x = cvt_pk_bf16(v0[0], v0[1]); w.y = cvt_pk_bf16(v0[2], v0[3]); w.z = cvt_pk_bf16(v1[0], v1[1]); w.w = cvt_pk_bf16(v1[2], v1[3]);
;                         if (pn >= 24) __builtin_nontemporal_store(w, (u32x4*)(dst + (size_t)row * ldc + col0 + bj * HALF)); else *(u32x4*)(dst + (size_t)row * ldc + col0 + bj * HALF) = w;
;                         if (kvo) { float* p = kvo + (size_t)(kvrow0 + row) * 1024 + col0 + bj * HALF; __builtin_nontemporal_store(v0, (f32x4*)p); __builtin_nontemporal_store(v1, (f32x4*)(p + 4)); }
;                     }
;                 } else if (wc == 0 && fq < 2) {
;                     const f32x4 v0 = acc[ai][0][m][0] * rs, v1 = acc[ai][0][m][1] * rs;
;                     float* p = FA + (size_t)row * 16 + 8 * fq; *(f32x4*)p = v0; *(f32x4*)(p + 4) = v1;
.Lfa_unit:
	v_lshrrev_b32_e32 v4, 6, v166
	v_lshrrev_b32_e32 v5, 5, v168
	v_and_b32_e32 v6, 15, v166
	v_bfe_u32 v7, v168, 3, 2
	s_nop 0
	v_readfirstlane_b32 s6, v4
	v_readfirstlane_b32 s11, v5
	s_nop 3
	s_lshl_b32 s6, s6, 2
	s_add_i32 s6, s6, s11
	s_lshl_b32 s6, s6, 5
	s_add_i32 s6, s6, s7
	v_add_u32_e32 v114, s6, v6
	v_lshlrev_b32_e32 v115, 4, v7
	v_lshl_add_u32 v108, v114, 11, v115
	v_mov_b32_e32 v109, 0
	v_lshl_add_u64 v[108:109], s[50:51], 0, v[108:109]
	s_mov_b64 s[14:15], 0x8000
	v_lshl_add_u64 v[110:111], v[108:109], 0, s[14:15]
	v_lshl_add_u32 v112, v6, 11, v115
	v_mov_b32_e32 v113, 0
	s_add_u32 s38, s52, 0x1000000
	s_addc_u32 s39, s53, 0
	v_lshl_add_u64 v[112:113], s[38:39], 0, v[112:113]
	v_lshlrev_b32_e32 v116, 6, v114
	v_mov_b32_e32 v117, 0
	v_lshl_add_u64 v[116:117], v[146:147], 0, v[116:117]
	global_load_dwordx4 v[118:121], v[116:117], off
	global_load_dwordx4 v[122:125], v[116:117], off offset:1024
	v_mov_b32_e32 v100, 0
	v_mov_b32_e32 v101, 0
	v_mov_b32_e32 v102, 0
	v_mov_b32_e32 v103, 0
	v_mov_b32_e32 v104, 0
	v_mov_b32_e32 v105, 0
	v_mov_b32_e32 v106, 0
	v_mov_b32_e32 v107, 0
	global_load_dwordx4 v[4:7], v[112:113], off
	global_load_dwordx4 v[8:11], v[112:113], off offset:64
	global_load_dwordx4 v[12:15], v[112:113], off offset:128
	global_load_dwordx4 v[16:19], v[112:113], off offset:192
	global_load_dwordx4 v[20:23], v[112:113], off offset:256
	global_load_dwordx4 v[24:27], v[112:113], off offset:320
	global_load_dwordx4 v[28:31], v[112:113], off offset:384
	global_load_dwordx4 v[32:35], v[112:113], off offset:448
	global_load_dwordx4 v[36:39], v[108:109], off
	global_load_dwordx4 v[40:43], v[108:109], off offset:64
	global_load_dwordx4 v[44:47], v[108:109], off offset:128
	global_load_dwordx4 v[48:51], v[108:109], off offset:192
	global_load_dwordx4 v[52:55], v[108:109], off offset:256
	global_load_dwordx4 v[56:59], v[108:109], off offset:320
	global_load_dwordx4 v[60:63], v[108:109], off offset:384
	global_load_dwordx4 v[64:67], v[108:109], off offset:448
	global_load_dwordx4 v[68:71], v[110:111], off
	global_load_dwordx4 v[72:75], v[110:111], off offset:64
	global_load_dwordx4 v[76:79], v[110:111], off offset:128
	global_load_dwordx4 v[80:83], v[110:111], off offset:192
	global_load_dwordx4 v[84:87], v[110:111], off offset:256
	global_load_dwordx4 v[88:91], v[110:111], off offset:320
	global_load_dwordx4 v[92:95], v[110:111], off offset:384
	global_load_dwordx4 v[96:99], v[110:111], off offset:448
	s_waitcnt vmcnt(0)
	v_mfma_f32_16x16x32_bf16 v[100:103], v[4:7], v[36:39], v[100:103]
	v_mfma_f32_16x16x32_bf16 v[104:107], v[4:7], v[68:71], v[104:107]
	v_mfma_f32_16x16x32_bf16 v[100:103], v[8:11], v[40:43], v[100:103]
	v_mfma_f32_16x16x32_bf16 v[104:107], v[8:11], v[72:75], v[104:107]
	v_mfma_f32_16x16x32_bf16 v[100:103], v[12:15], v[44:47], v[100:103]
	v_mfma_f32_16x16x32_bf16 v[104:107], v[12:15], v[76:79], v[104:107]
	v_mfma_f32_16x16x32_bf16 v[100:103], v[16:19], v[48:51], v[100:103]
	v_mfma_f32_16x16x32_bf16 v[104:107], v[16:19], v[80:83], v[104:107]
	v_mfma_f32_16x16x32_bf16 v[100:103], v[20:23], v[52:55], v[100:103]
	v_mfma_f32_16x16x32_bf16 v[104:107], v[20:23], v[84:87], v[104:107]
	v_mfma_f32_16x16x32_bf16 v[100:103], v[24:27], v[56:59], v[100:103]
	v_mfma_f32_16x16x32_bf16 v[104:107], v[24:27], v[88:91], v[104:107]
	v_mfma_f32_16x16x32_bf16 v[100:103], v[28:31], v[60:63], v[100:103]
	v_mfma_f32_16x16x32_bf16 v[104:107], v[28:31], v[92:95], v[104:107]
	v_mfma_f32_16x16x32_bf16 v[100:103], v[32:35], v[64:67], v[100:103]
	v_mfma_f32_16x16x32_bf16 v[104:107], v[32:35], v[96:99], v[104:107]
	global_load_dwordx4 v[4:7], v[112:113], off offset:512
	global_load_dwordx4 v[8:11], v[112:113], off offset:576
	global_load_dwordx4 v[12:15], v[112:113], off offset:640
	global_load_dwordx4 v[16:19], v[112:113], off offset:704
	global_load_dwordx4 v[20:23], v[112:113], off offset:768
	global_load_dwordx4 v[24:27], v[112:113], off offset:832
	global_load_dwordx4 v[28:31], v[112:113], off offset:896
	global_load_dwordx4 v[32:35], v[112:113], off offset:960
	global_load_dwordx4 v[36:39], v[108:109], off offset:512
	global_load_dwordx4 v[40:43], v[108:109], off offset:576
	global_load_dwordx4 v[44:47], v[108:109], off offset:640
	global_load_dwordx4 v[48:51], v[108:109], off offset:704
	global_load_dwordx4 v[52:55], v[108:109], off offset:768
	global_load_dwordx4 v[56:59], v[108:109], off offset:832
	global_load_dwordx4 v[60:63], v[108:109], off offset:896
	global_load_dwordx4 v[64:67], v[108:109], off offset:960
	global_load_dwordx4 v[68:71], v[110:111], off offset:512
	global_load_dwordx4 v[72:75], v[110:111], off offset:576
	global_load_dwordx4 v[76:79], v[110:111], off offset:640
	global_load_dwordx4 v[80:83], v[110:111], off offset:704
	global_load_dwordx4 v[84:87], v[110:111], off offset:768
	global_load_dwordx4 v[88:91], v[110:111], off offset:832
	global_load_dwordx4 v[92:95], v[110:111], off offset:896
	global_load_dwordx4 v[96:99], v[110:111], off offset:960
	s_waitcnt vmcnt(0)
	v_mfma_f32_16x16x32_bf16 v[100:103], v[4:7], v[36:39], v[100:103]
	v_mfma_f32_16x16x32_bf16 v[104:107], v[4:7], v[68:71], v[104:107]
	v_mfma_f32_16x16x32_bf16 v[100:103], v[8:11], v[40:43], v[100:103]
	v_mfma_f32_16x16x32_bf16 v[104:107], v[8:11], v[72:75], v[104:107]
	v_mfma_f32_16x16x32_bf16 v[100:103], v[12:15], v[44:47], v[100:103]
	v_mfma_f32_16x16x32_bf16 v[104:107], v[12:15], v[76:79], v[104:107]
	v_mfma_f32_16x16x32_bf16 v[100:103], v[16:19], v[48:51], v[100:103]
	v_mfma_f32_16x16x32_bf16 v[104:107], v[16:19], v[80:83], v[104:107]
	v_mfma_f32_16x16x32_bf16 v[100:103], v[20:23], v[52:55], v[100:103]
	v_mfma_f32_16x16x32_bf16 v[104:107], v[20:23], v[84:87], v[104:107]
	v_mfma_f32_16x16x32_bf16 v[100:103], v[24:27], v[56:59], v[100:103]
	v_mfma_f32_16x16x32_bf16 v[104:107], v[24:27], v[88:91], v[104:107]
	v_mfma_f32_16x16x32_bf16 v[100:103], v[28:31], v[60:63], v[100:103]
	v_mfma_f32_16x16x32_bf16 v[104:107], v[28:31], v[92:95], v[104:107]
	v_mfma_f32_16x16x32_bf16 v[100:103], v[32:35], v[64:67], v[100:103]
	v_mfma_f32_16x16x32_bf16 v[104:107], v[32:35], v[96:99], v[104:107]
	global_load_dwordx4 v[4:7], v[112:113], off offset:1024
	global_load_dwordx4 v[8:11], v[112:113], off offset:1088
	global_load_dwordx4 v[12:15], v[112:113], off offset:1152
	global_load_dwordx4 v[16:19], v[112:113], off offset:1216
	global_load_dwordx4 v[20:23], v[112:113], off offset:1280
	global_load_dwordx4 v[24:27], v[112:113], off offset:1344
	global_load_dwordx4 v[28:31], v[112:113], off offset:1408
	global_load_dwordx4 v[32:35], v[112:113], off offset:1472
	global_load_dwordx4 v[36:39], v[108:109], off offset:1024
	global_load_dwordx4 v[40:43], v[108:109], off offset:1088
	global_load_dwordx4 v[44:47], v[108:109], off offset:1152
	global_load_dwordx4 v[48:51], v[108:109], off offset:1216
	global_load_dwordx4 v[52:55], v[108:109], off offset:1280
	global_load_dwordx4 v[56:59], v[108:109], off offset:1344
	global_load_dwordx4 v[60:63], v[108:109], off offset:1408
	global_load_dwordx4 v[64:67], v[108:109], off offset:1472
	global_load_dwordx4 v[68:71], v[110:111], off offset:1024
	global_load_dwordx4 v[72:75], v[110:111], off offset:1088
	global_load_dwordx4 v[76:79], v[110:111], off offset:1152
	global_load_dwordx4 v[80:83], v[110:111], off offset:1216
	global_load_dwordx4 v[84:87], v[110:111], off offset:1280
	global_load_dwordx4 v[88:91], v[110:111], off offset:1344
	global_load_dwordx4 v[92:95], v[110:111], off offset:1408
	global_load_dwordx4 v[96:99], v[110:111], off offset:1472
	s_waitcnt vmcnt(0)
	v_mfma_f32_16x16x32_bf16 v[100:103], v[4:7], v[36:39], v[100:103]
	v_mfma_f32_16x16x32_bf16 v[104:107], v[4:7], v[68:71], v[104:107]
	v_mfma_f32_16x16x32_bf16 v[100:103], v[8:11], v[40:43], v[100:103]
	v_mfma_f32_16x16x32_bf16 v[104:107], v[8:11], v[72:75], v[104:107]
	v_mfma_f32_16x16x32_bf16 v[100:103], v[12:15], v[44:47], v[100:103]
	v_mfma_f32_16x16x32_bf16 v[104:107], v[12:15], v[76:79], v[104:107]
	v_mfma_f32_16x16x32_bf16 v[100:103], v[16:19], v[48:51], v[100:103]
	v_mfma_f32_16x16x32_bf16 v[104:107], v[16:19], v[80:83], v[104:107]
	v_mfma_f32_16x16x32_bf16 v[100:103], v[20:23], v[52:55], v[100:103]
	v_mfma_f32_16x16x32_bf16 v[104:107], v[20:23], v[84:87], v[104:107]
	v_mfma_f32_16x16x32_bf16 v[100:103], v[24:27], v[56:59], v[100:103]
	v_mfma_f32_16x16x32_bf16 v[104:107], v[24:27], v[88:91], v[104:107]
	v_mfma_f32_16x16x32_bf16 v[100:103], v[28:31], v[60:63], v[100:103]
	v_mfma_f32_16x16x32_bf16 v[104:107], v[28:31], v[92:95], v[104:107]
	v_mfma_f32_16x16x32_bf16 v[100:103], v[32:35], v[64:67], v[100:103]
	v_mfma_f32_16x16x32_bf16 v[104:107], v[32:35], v[96:99], v[104:107]
	global_load_dwordx4 v[4:7], v[112:113], off offset:1536
	global_load_dwordx4 v[8:11], v[112:113], off offset:1600
	global_load_dwordx4 v[12:15], v[112:113], off offset:1664
	global_load_dwordx4 v[16:19], v[112:113], off offset:1728
	global_load_dwordx4 v[20:23], v[112:113], off offset:1792
	global_load_dwordx4 v[24:27], v[112:113], off offset:1856
	global_load_dwordx4 v[28:31], v[112:113], off offset:1920
	global_load_dwordx4 v[32:35], v[112:113], off offset:1984
	global_load_dwordx4 v[36:39], v[108:109], off offset:1536
	global_load_dwordx4 v[40:43], v[108:109], off offset:1600
	global_load_dwordx4 v[44:47], v[108:109], off offset:1664
	global_load_dwordx4 v[48:51], v[108:109], off offset:1728
	global_load_dwordx4 v[52:55], v[108:109], off offset:1792
	global_load_dwordx4 v[56:59], v[108:109], off offset:1856
	global_load_dwordx4 v[60:63], v[108:109], off offset:1920
	global_load_dwordx4 v[64:67], v[108:109], off offset:1984
	global_load_dwordx4 v[68:71], v[110:111], off offset:1536
	global_load_dwordx4 v[72:75], v[110:111], off offset:1600
	global_load_dwordx4 v[76:79], v[110:111], off offset:1664
	global_load_dwordx4 v[80:83], v[110:111], off offset:1728
	global_load_dwordx4 v[84:87], v[110:111], off offset:1792
	global_load_dwordx4 v[88:91], v[110:111], off offset:1856
	global_load_dwordx4 v[92:95], v[110:111], off offset:1920
	global_load_dwordx4 v[96:99], v[110:111], off offset:1984
	s_waitcnt vmcnt(0)
; __device__ __forceinline__ float rstd_from_ss(const float* ssrow, int fq) {
;     const f32x4 a = ((const f32x4*)ssrow)[fq];
;     float s = (a[0] + a[1]) + (a[2] + a[3]);
;     s += __shfl_xor(s, 16); s += __shfl_xor(s, 32);
;     return rsqrtf(s * (1.0f / 1024.0f) + 1e-6f);
; }
;     __device__ __forceinline__ void operator()(const f32x4 (&acc)[2][2][4][2], const Unit& u, int wr, int wc, int fr, int fq) const {
;     ...
;                 } else if (wc == 0 && fq < 2) {
;                     const f32x4 v0 = acc[ai][0][m][0] * rs, v1 = acc[ai][0][m][1] * rs;
;                     float* p = FA + (size_t)row * 16 + 8 * fq; *(f32x4*)p = v0; *(f32x4*)(p + 4) = v1;
	v_mfma_f32_16x16x32_bf16 v[100:103], v[4:7], v[36:39], v[100:103]
	v_mfma_f32_16x16x32_bf16 v[104:107], v[4:7], v[68:71], v[104:107]
	v_mfma_f32_16x16x32_bf16 v[100:103], v[8:11], v[40:43], v[100:103]
	v_mfma_f32_16x16x32_bf16 v[104:107], v[8:11], v[72:75], v[104:107]
	v_mfma_f32_16x16x32_bf16 v[100:103], v[12:15], v[44:47], v[100:103]
	v_mfma_f32_16x16x32_bf16 v[104:107], v[12:15], v[76:79], v[104:107]
	v_mfma_f32_16x16x32_bf16 v[100:103], v[16:19], v[48:51], v[100:103]
	v_mfma_f32_16x16x32_bf16 v[104:107], v[16:19], v[80:83], v[104:107]
	v_mfma_f32_16x16x32_bf16 v[100:103], v[20:23], v[52:55], v[100:103]
	v_mfma_f32_16x16x32_bf16 v[104:107], v[20:23], v[84:87], v[104:107]
	v_mfma_f32_16x16x32_bf16 v[100:103], v[24:27], v[56:59], v[100:103]
	v_mfma_f32_16x16x32_bf16 v[104:107], v[24:27], v[88:91], v[104:107]
	v_mfma_f32_16x16x32_bf16 v[100:103], v[28:31], v[60:63], v[100:103]
	v_mfma_f32_16x16x32_bf16 v[104:107], v[28:31], v[92:95], v[104:107]
	v_mfma_f32_16x16x32_bf16 v[100:103], v[32:35], v[64:67], v[100:103]
	v_mfma_f32_16x16x32_bf16 v[104:107], v[32:35], v[96:99], v[104:107]
	v_add_f32_e32 v118, v119, v118
	v_add_f32_e32 v119, v120, v121
	v_add_f32_e32 v118, v118, v119
	ds_bpermute_b32 v119, v199, v118
	s_waitcnt lgkmcnt(0)
	v_add_f32_e32 v118, v118, v119
	ds_bpermute_b32 v119, v200, v118
	s_waitcnt lgkmcnt(0)
	v_add_f32_e32 v118, v118, v119
	v_fmamk_f32 v118, v118, 0x3a800000, v140
	v_cmp_gt_f32_e32 vcc, s92, v118
	v_mul_f32_e32 v119, 0x4b800000, v118
	s_nop 0
	v_cndmask_b32_e32 v118, v118, v119, vcc
	v_rsq_f32_e32 v118, v118
	s_nop 0
	v_mul_f32_e32 v119, 0x45800000, v118
	v_cndmask_b32_e32 v118, v118, v119, vcc
	v_add_f32_e32 v122, v123, v122
	v_add_f32_e32 v123, v124, v125
	v_add_f32_e32 v122, v122, v123
	ds_bpermute_b32 v123, v199, v122
	s_waitcnt lgkmcnt(0)
	v_add_f32_e32 v122, v122, v123
	ds_bpermute_b32 v123, v200, v122
	s_waitcnt lgkmcnt(0)
	v_add_f32_e32 v122, v122, v123
	v_fmamk_f32 v122, v122, 0x3a800000, v140
	v_cmp_gt_f32_e32 vcc, s92, v122
	v_mul_f32_e32 v123, 0x4b800000, v122
	s_nop 0
	v_cndmask_b32_e32 v122, v122, v123, vcc
	v_rsq_f32_e32 v122, v122
	s_nop 0
	v_mul_f32_e32 v123, 0x45800000, v122
	v_cndmask_b32_e32 v122, v122, v123, vcc
	v_mul_f32_e32 v100, v100, v118
	v_mul_f32_e32 v101, v101, v118
	v_mul_f32_e32 v102, v102, v118
	v_mul_f32_e32 v103, v103, v118
	v_mul_f32_e32 v104, v104, v122
	v_mul_f32_e32 v105, v105, v122
	v_mul_f32_e32 v106, v106, v122
	v_mul_f32_e32 v107, v107, v122
	v_sub_co_u32_e32 v126, vcc, v148, v115
	s_nop 1
	v_subbrev_co_u32_e32 v127, vcc, 0, v149, vcc
	v_lshlrev_b32_e32 v128, 6, v114
	v_mov_b32_e32 v129, 0
	v_lshl_add_u64 v[126:127], v[126:127], 0, v[128:129]
	global_store_dwordx4 v[126:127], v[100:103], off
	global_store_dwordx4 v[126:127], v[104:107], off offset:1024
	s_branch .LBB0_446
